# best + one static s_setprio 1 for waves 4-7 during the attention phases (4, 11, 14), reset at every phase start
# baseline (speedup 1.0000x reference)
; #define KARG_OUT() KARG_PTR(float*, 31)
; #define KARG_WS() KARG_PTR(unsigned char*, 32)
; __global__ void __launch_bounds__(NTHREADS, 2) fwd_megakernel(Args args) {
;     ...
;     for (int ph = ph_lo; ph < ph_hi;) {
;         int tid = threadIdx.x; asm volatile("" : "+v"(tid));
;         const int lane = tid & 63, wave = __builtin_amdgcn_readfirstlane(tid >> 6);
;         int G = gridDim.x, bx = blockIdx.x; asm volatile("" : "+s"(G), "+s"(bx));
;         const int bxg = __builtin_amdgcn_readfirstlane(xbar.st[5] ? (int)xbar.st[4] : bx);
;         const int gw = bx * NWAVES + wave, NGW = G * NWAVES;
;         unsigned char* ws = KARG_WS();
;         unsigned char* wb = (unsigned char*)KARG_OUT();
;         bf16_t* XN = (bf16_t*)(ws + WS_XN); bf16_t* BIG = (bf16_t*)(ws + WS_BIG); bf16_t* AB = (bf16_t*)(ws + WS_AB);
;         float* SSP = (float*)(ws + WS_SSP);
;         if (ph == 0) {
.LBB0_11:
	s_ashr_i32 s3, s2, 6
	s_setprio 0
	s_mov_b32 s4, 0x4810
	s_bitcmp1_b32 s4, s84
	s_cbranch_scc0 .Lattn_prio_skip
	s_cmp_lt_u32 s3, 4
	s_cbranch_scc1 .Lattn_prio_skip
	s_setprio 1
.Lattn_prio_skip:
	s_lshl_b32 s2, s87, 3
	s_load_dwordx2 s[30:31], s[0:1], 0x100
	v_writelane_b32 v255, s3, 13
	s_add_i32 s28, s2, s3
	s_load_dwordx2 s[2:3], s[0:1], 0xf8
	s_lshl_b32 s36, s14, 3
	v_and_b32_e32 v158, 63, v205
	s_waitcnt lgkmcnt(0)
	v_readfirstlane_b32 s16, v0
	v_writelane_b32 v255, s2, 14
	s_nop 1
	v_writelane_b32 v255, s3, 15
	s_add_u32 s2, s30, 0x1e100000
	s_addc_u32 s3, s31, 0
	v_writelane_b32 v255, s2, 16
	s_cmp_lg_u32 s84, 0
	s_nop 0
	v_writelane_b32 v255, s3, 17
	s_cselect_b64 s[2:3], -1, 0
	v_writelane_b32 v255, s2, 18
	s_and_b64 vcc, exec, s[2:3]
	s_nop 0
	v_writelane_b32 v255, s3, 19
	s_cbranch_vccz .LBB0_15
	s_add_u32 s56, s30, 0x8000000
	s_addc_u32 s57, s31, 0
	s_cmp_lt_i32 s84, 8
	s_cbranch_scc1 .LBB0_16
	s_cmp_gt_i32 s84, 15
	s_cbranch_scc0 .LBB0_17
	s_cmp_eq_u32 s84, 16
	s_mov_b64 s[2:3], -1
	s_cselect_b64 s[4:5], -1, 0
	s_cbranch_execz .LBB0_18
	s_branch .LBB0_19
